# v39 + attention softmax chain: running-max+8 add hoisted into the post-QK MFMA hazard window (size-neutral reorder)
# baseline (speedup 1.0000x reference)
; #define LAS __attribute__((address_space(3)))
; __device__ __forceinline__ void attn_unit(int b, int h, int qb, const bf16_t* __restrict__ Q, const bf16_t* __restrict__ K, const bf16_t* __restrict__ VT, const float* __restrict__ kmean,
;                                           bf16_t* __restrict__ O, LAS unsigned char* lds) {
;     ...
;             float rm = fmaxf(p0[0], p1[0]);
; #pragma unroll
;             for (int r = 1; r < 16; ++r) rm = fmaxf(rm, fmaxf(p0[r], p1[r]));
;             { const auto rr = __builtin_amdgcn_permlane32_swap(__float_as_uint(rm), __float_as_uint(rm), false, false); rm = fmaxf(__uint_as_float(rr[0]), __uint_as_float(rr[1])); }
;             rm = rowsel ? rm : NEGBIG;
;             const bool grow = rm > mrun + 8.0f;
;             const float mnew = grow ? rm : mrun;
;             const float alpha = grow ? __builtin_amdgcn_exp2f(mrun - mnew) : 1.0f;
;             mrun = mnew;
;             const float msub = rowsel ? mnew : 1e30f;
;             float sum = 0.f;
; #pragma unroll
;             for (int r = 0; r < 16; ++r) { p0[r] = __builtin_amdgcn_exp2f(p0[r] - msub); p1[r] = __builtin_amdgcn_exp2f(p1[r] - msub); sum += p0[r] + p1[r]; }
;             lrun = lrun * alpha + sum;
;             if (__any(grow)) {
;                 if (hi == 0) wsf[r32] = alpha;
;                 asm volatile("s_waitcnt lgkmcnt(0)" ::: "memory");
; #pragma unroll
;                 for (int gq = 0; gq < 4; ++gq) { const f32x4 a = *(const LAS f32x4*)(wsf + 8 * gq + 4 * hi);
; #pragma unroll
;                     for (int d = 0; d < 4; ++d) { o[d][4 * gq + 0] *= a[0]; o[d][4 * gq + 1] *= a[1]; o[d][4 * gq + 2] *= a[2]; o[d][4 * gq + 3] *= a[3]; } }
.LBB0_458:
	v_add_f32_e32 v207, 0x41000000, v203
	s_nop 8
	v_max3_f32 v202, v64, v65, v66
	v_max3_f32 v204, v67, v68, v69
	v_max3_f32 v205, v70, v71, v72
	v_max3_f32 v206, v73, v74, v75
	v_max3_f32 v202, v202, v76, v77
	v_max3_f32 v204, v204, v78, v79
	v_max3_f32 v205, v205, v80, v81
	v_max3_f32 v206, v206, v82, v83
	v_max3_f32 v202, v202, v84, v85
	v_max3_f32 v204, v204, v86, v87
	v_max3_f32 v205, v205, v88, v89
	v_max3_f32 v206, v206, v90, v91
	v_max3_f32 v202, v202, v92, v93
	v_max3_f32 v204, v204, v94, v95
	v_max3_f32 v202, v202, v204, v205
	v_max_f32_e32 v202, v202, v206
	v_mov_b32_e32 v204, v202
	s_nop 1
	v_permlane32_swap_b32_e32 v202, v204
	v_max_f32_e32 v202, v202, v204
	v_cndmask_b32_e64 v202, v202, v185, s[8:9]
	v_cmp_gt_f32_e32 vcc, v202, v207
	s_nop 1
	v_cndmask_b32_e32 v202, v203, v202, vcc
	v_sub_f32_e32 v203, v203, v202
	v_exp_f32_e32 v203, v203
	s_nop 0
	v_cndmask_b32_e32 v203, 1.0, v203, vcc
	s_cbranch_vccz .LBB0_462
	s_and_saveexec_b64 s[70:71], s[6:7]
	ds_write_b32 v192, v203
	s_or_b64 exec, exec, s[70:71]
	s_waitcnt lgkmcnt(0)
	v_add_u32_e32 v216, s95, v178
	ds_read_b128 v[204:207], v216 offset:96
	ds_read_b128 v[208:211], v216 offset:64
	ds_read_b128 v[212:215], v216 offset:32
	ds_read_b128 v[216:219], v216
	s_waitcnt lgkmcnt(0)
	s_waitcnt lgkmcnt(3)
	v_pk_mul_f32 v[60:61], v[60:61], v[204:205]
	s_waitcnt lgkmcnt(2)
	v_pk_mul_f32 v[56:57], v[56:57], v[208:209]
	s_waitcnt lgkmcnt(1)
	v_pk_mul_f32 v[52:53], v[52:53], v[212:213]
	v_pk_mul_f32 v[62:63], v[62:63], v[206:207]
	v_pk_mul_f32 v[58:59], v[58:59], v[210:211]
	v_pk_mul_f32 v[54:55], v[54:55], v[214:215]
	s_waitcnt lgkmcnt(0)
	v_pk_mul_f32 v[50:51], v[50:51], v[218:219]
	v_pk_mul_f32 v[48:49], v[48:49], v[216:217]
	v_pk_mul_f32 v[44:45], v[44:45], v[204:205]
	v_pk_mul_f32 v[40:41], v[40:41], v[208:209]
	v_pk_mul_f32 v[36:37], v[36:37], v[212:213]
	v_pk_mul_f32 v[46:47], v[46:47], v[206:207]
	v_pk_mul_f32 v[42:43], v[42:43], v[210:211]
	v_pk_mul_f32 v[38:39], v[38:39], v[214:215]
	v_pk_mul_f32 v[34:35], v[34:35], v[218:219]
	v_pk_mul_f32 v[32:33], v[32:33], v[216:217]
	v_pk_mul_f32 v[28:29], v[28:29], v[204:205]
	v_pk_mul_f32 v[24:25], v[24:25], v[208:209]
	v_pk_mul_f32 v[20:21], v[20:21], v[212:213]
	v_pk_mul_f32 v[30:31], v[30:31], v[206:207]
	v_pk_mul_f32 v[26:27], v[26:27], v[210:211]
	v_pk_mul_f32 v[22:23], v[22:23], v[214:215]
	v_pk_mul_f32 v[18:19], v[18:19], v[218:219]
	v_pk_mul_f32 v[16:17], v[16:17], v[216:217]
	v_pk_mul_f32 v[12:13], v[12:13], v[204:205]
	v_pk_mul_f32 v[8:9], v[8:9], v[208:209]
	v_pk_mul_f32 v[4:5], v[4:5], v[212:213]
	v_pk_mul_f32 v[14:15], v[14:15], v[206:207]
	v_pk_mul_f32 v[10:11], v[10:11], v[210:211]
	v_pk_mul_f32 v[6:7], v[6:7], v[214:215]
	v_pk_mul_f32 v[2:3], v[2:3], v[218:219]
	v_pk_mul_f32 v[0:1], v[0:1], v[216:217]
